# attention+pool phase: one static s_setprio 1 for waves 4-7 (younger half), reset at the phase end
# baseline (speedup 1.0000x reference)
; __device__ __forceinline__ void attn_phase(LAS unsigned char* lds, const bf16* PROJ, bf16* CONCAT, const float* sinks) {
;     ...
;     bf16x8 qf[4][2];
;     ...
;     const bool xmap = (gridDim.x == 256);
;     ...
;     if ((int)blockIdx.x < NB * 64 * 2) { ATT_LOAD_KV(ATT_UNIT((int)blockIdx.x)); ATT_LOAD_Q(ATT_UNIT((int)blockIdx.x)); }
.LBB0_267:
	v_or_b32_e32 v2, 0x80, v128
	v_mov_b32_e32 v3, v1
	v_lshl_add_u64 v[20:21], s[38:39], 0, v[2:3]
	v_or_b32_e32 v130, 0xc0, v128
	v_mov_b32_e32 v131, v1
	v_mad_u64_u32 v[24:25], s[0:1], v20, s85, v[28:29]
	v_lshl_add_u64 v[30:31], s[38:39], 0, v[130:131]
	v_mov_b32_e32 v0, v25
	v_mad_u64_u32 v[28:29], s[0:1], v30, s85, v[28:29]
	v_mad_u64_u32 v[20:21], s[0:1], v21, s85, v[0:1]
	v_mov_b32_e32 v0, v29
	v_mad_u64_u32 v[30:31], s[0:1], v31, s85, v[0:1]
	v_mov_b32_e32 v25, v20
	v_mov_b32_e32 v29, v30
	v_ashrrev_i32_e32 v133, 7, v70
	v_readlane_b32 s0, v245, 40
	global_load_dwordx4 v[20:23], v[24:25], off offset:1024
	s_nop 0
	global_load_dwordx4 v[24:27], v[24:25], off offset:1280
	s_nop 0
	global_load_dwordx4 v[64:67], v[28:29], off offset:1024
	global_load_dwordx4 v[60:63], v[28:29], off offset:1280
	v_add_lshl_u32 v28, v133, s0, 6
	v_ashrrev_i32_e32 v29, 31, v28
	v_bitop3_b32 v132, v70, 15, 64 bitop3:0xe0
	v_readlane_b32 s0, v245, 41
	v_lshl_add_u64 v[28:29], v[28:29], 1, s[74:75]
	v_and_b32_e32 v0, 48, v128
	v_or_b32_e32 v30, s0, v132
	v_readlane_b32 s16, v245, 34
	v_lshl_add_u64 v[28:29], v[28:29], 0, v[0:1]
	v_readlane_b32 s17, v245, 35
	v_or_b32_e32 v30, s16, v30
	v_mad_u64_u32 v[32:33], s[0:1], v30, s85, v[28:29]
	s_mov_b32 s0, 0x1e000
	v_mad_i32_i24 v33, s17, v195, v33
	v_add_co_u32_e32 v28, vcc, s0, v32
	s_mov_b32 s0, 0x14000
	s_nop 0
	v_addc_co_u32_e32 v29, vcc, 0, v33, vcc
	global_load_dwordx4 v[52:55], v[28:29], off offset:64 nt
	global_load_dwordx4 v[56:59], v[28:29], off nt
	v_add_co_u32_e32 v28, vcc, s0, v32
	s_mov_b32 s0, 0xa000
	s_nop 0
	v_addc_co_u32_e32 v29, vcc, 0, v33, vcc
	global_load_dwordx4 v[44:47], v[28:29], off offset:64 nt
	global_load_dwordx4 v[48:51], v[28:29], off nt
	v_add_co_u32_e32 v28, vcc, s0, v32
	v_lshlrev_b32_e32 v75, 1, v68
	s_nop 0
	v_addc_co_u32_e32 v29, vcc, 0, v33, vcc
	global_load_dwordx4 v[36:39], v[28:29], off offset:64 nt
	global_load_dwordx4 v[40:43], v[28:29], off nt
	s_nop 0
	global_load_dwordx4 v[28:31], v[32:33], off offset:64 nt
	s_nop 0
	global_load_dwordx4 v[32:35], v[32:33], off nt
	v_lshl_add_u64 v[136:137], v[68:69], 1, s[74:75]
	v_and_b32_e32 v68, 48, v70
	v_and_b32_e32 v69, 64, v196
	v_add_u32_e32 v76, 0, v68
	v_xor_b32_e32 v68, 16, v196
	v_add_u32_e32 v69, 64, v69
	v_cmp_lt_i32_e32 vcc, v68, v69
	v_lshrrev_b32_e32 v73, 4, v128
	s_mov_b32 s23, s77
	v_cndmask_b32_e32 v68, v196, v68, vcc
	v_lshlrev_b32_e32 v135, 2, v68
	v_xor_b32_e32 v68, 32, v196
	v_cmp_lt_i32_e32 vcc, v68, v69
	v_readlane_b32 s36, v246, 27
	v_lshlrev_b32_e32 v74, 3, v73
	v_cndmask_b32_e32 v68, v196, v68, vcc
	v_lshlrev_b32_e32 v73, 2, v73
	v_lshlrev_b32_e32 v148, 2, v68
	v_bfe_u32 v68, v70, 2, 2
	s_lshl_b64 s[0:1], s[22:23], 2
	v_readlane_b32 s50, v246, 41
	v_or_b32_e32 v77, v73, v68
	v_lshlrev_b32_e32 v68, 3, v70
	v_lshl_add_u64 v[140:141], s[74:75], 0, v[0:1]
	v_mul_u32_u24_e32 v0, 0x48, v128
	v_readlane_b32 s51, v246, 42
	s_add_u32 s0, s50, s0
	v_and_b32_e32 v68, 24, v68
	v_lshlrev_b32_e32 v0, 1, v0
	s_movk_i32 s16, 0x1200
	s_addc_u32 s1, s51, s1
	v_add_u32_e32 v78, 0, v68
	v_lshlrev_b32_e32 v68, 4, v70
	v_add3_u32 v149, 0, v75, v0
	v_mul_lo_u32 v0, v71, s16
	s_add_i32 s16, 0, 0x12000
	v_and_b32_e32 v68, 0x70, v68
	v_mov_b32_e32 v69, v1
	v_add_u32_e32 v0, s16, v0
	v_readlane_b32 s42, v246, 33
	v_readlane_b32 s43, v246, 34
	v_and_b32_e32 v72, 15, v70
	v_lshl_add_u64 v[138:139], s[24:25], 0, v[68:69]
	v_add_u32_e32 v69, v0, v68
	v_or_b32_e32 v68, 2, v73
	v_readlane_b32 s44, v246, 35
	v_readlane_b32 s45, v246, 36
	v_and_b32_e32 v134, 64, v70
	v_cmp_lt_u32_e64 s[42:43], v72, v68
	v_or_b32_e32 v68, 3, v73
	v_readlane_b32 s38, v246, 29
	v_readlane_b32 s39, v246, 30
	v_readlane_b32 s40, v246, 31
	v_readlane_b32 s41, v246, 32
	v_readlane_b32 s48, v246, 39
	v_readlane_b32 s49, v246, 40
	v_lshrrev_b32_e32 v80, 3, v128
	v_cmp_lt_u32_e64 s[44:45], v72, v68
	v_or_b32_e32 v68, v77, v134
	v_or_b32_e32 v75, 32, v134
	v_mul_u32_u24_e32 v79, 0x90, v72
	v_cmp_lt_u32_e64 s[38:39], v72, v73
	v_cmp_ge_u32_e64 s[40:41], v73, v72
	v_cmp_lt_u32_e64 s[48:49], v73, v72
	v_mul_u32_u24_e32 v73, 0x90, v68
	v_or_b32_e32 v68, 8, v80
	v_or_b32_e32 v72, v75, v72
	v_or_b32_e32 v75, v75, v77
	v_readlane_b32 s46, v246, 37
	v_readlane_b32 s47, v246, 38
	v_mul_u32_u24_e32 v70, 0x90, v80
	v_mul_u32_u24_e32 v71, 0x90, v132
	v_add3_u32 v150, v0, v79, v74
	v_lshlrev_b32_e32 v0, 10, v80
	v_mul_u32_u24_e32 v74, 0x90, v68
	v_lshlrev_b32_e32 v68, 10, v68
	v_mul_u32_u24_e32 v72, 0x90, v72
	v_mul_u32_u24_e32 v75, 0x90, v75
	v_cmp_ne_u32_e64 s[46:47], 0, v134
	v_add_u32_e32 v151, v76, v71
	v_add_u32_e32 v152, v78, v73
	v_add_u32_e32 v153, v69, v70
	v_lshlrev_b32_e32 v0, 1, v0
	v_add_u32_e32 v154, v69, v74
	v_lshlrev_b32_e32 v142, 1, v68
	v_add_u32_e32 v155, v76, v72
	v_add_u32_e32 v156, v78, v75
	v_readlane_b32 s16, v245, 27
	s_mov_b32 s23, s2
	v_readlane_b32 s37, v246, 28
	v_readfirstlane_b32 s100, v192
	s_nop 3
	s_lshr_b32 s100, s100, 6
	s_cmp_ge_u32 s100, 4
	s_cbranch_scc0 .Lattn_prio_done
	s_setprio 1
.Lattn_prio_done:
	s_branch .LBB0_269
.LBB0_268:
	v_readlane_b32 s23, v244, 14
	s_add_i32 s16, s16, s23
	s_andn2_b64 vcc, exec, s[62:63]
	s_mov_b32 s23, s17
	s_barrier
	s_cbranch_vccz .LBB0_280

; __device__ __forceinline__ void xcd_barrier(const XcdBarrier& b) {
;     asm volatile("s_waitcnt vmcnt(0)" ::: "memory");
;     __syncthreads();
;     if (threadIdx.x == 0) {
;         unsigned* bar = b.bar;
;         __builtin_amdgcn_s_waitcnt(0);
;         unsigned nloc = b.st[0], nx = b.st[1];
;         if (nloc == 0u) { xcd_barrier_complete(bar, b.x, nloc, nx); b.st[0] = nloc; b.st[1] = nx; }
; __device__ __forceinline__ void pool_phase(LAS unsigned char* lds, const bf16* PROJ, bf16* CONCAT) {
;     ...
;     __syncthreads();
.LBB0_378:
	s_waitcnt lgkmcnt(0)
	s_barrier
	s_waitcnt vmcnt(0)
	v_readlane_b32 s62, v246, 43
	v_readlane_b32 s63, v246, 44
	s_setprio 0
	s_barrier
	s_and_saveexec_b64 s[0:1], s[62:63]
	v_readlane_b32 s56, v246, 2
	v_readlane_b32 s48, v245, 24
	v_readlane_b32 s57, v246, 3
	s_cbranch_execz .LBB0_430
	v_readlane_b32 s16, v244, 19
	s_waitcnt vmcnt(0) expcnt(0) lgkmcnt(0)
	s_nop 0
	v_mov_b32_e32 v0, s16
	ds_read_b32 v3, v0
	v_readlane_b32 s16, v244, 20
	s_waitcnt lgkmcnt(0)
	v_cmp_ne_u32_e32 vcc, 0, v3
	v_mov_b32_e32 v0, s16
	ds_read_b32 v2, v0
	s_cbranch_vccnz .LBB0_394
	s_mov_b32 s23, 1
	s_branch .LBB0_382
